# GQA loop: LDS-DMA issue clump split (second tile's pieces issued inside the PV section instead of one 40-instruction scalar block)
# baseline (speedup 1.0000x reference)
.LBB0_590:
	s_waitcnt lgkmcnt(2)
	v_mfma_f32_32x32x16_bf16 v[16:31], v[128:131], v[48:51], v[16:31]
	ds_read_b64_tr_b16 v[56:57], v15 offset:2048
	ds_read_b64_tr_b16 v[58:59], v15 offset:3072
	v_mfma_f32_16x16x32_bf16 v[144:147], v[2:5], v[140:143], v[144:147]
	v_exp_f32_e32 v96, v96
	v_exp_f32_e32 v97, v97
	v_exp_f32_e32 v98, v98
	v_exp_f32_e32 v99, v99
	s_waitcnt lgkmcnt(2)
	v_mfma_f32_32x32x16_bf16 v[32:47], v[128:131], v[52:55], v[32:47]
	ds_read_b64_tr_b16 v[48:49], v15 offset:2560
	ds_read_b64_tr_b16 v[50:51], v15 offset:3584
	v_exp_f32_e32 v100, v100
	v_exp_f32_e32 v101, v101
	v_exp_f32_e32 v102, v102
	v_exp_f32_e32 v103, v103
	s_waitcnt lgkmcnt(2)
	v_mfma_f32_32x32x16_bf16 v[16:31], v[10:13], v[56:59], v[16:31]
	ds_read_b64_tr_b16 v[52:53], v15 offset:4096
	ds_read_b64_tr_b16 v[54:55], v15 offset:5120
	v_exp_f32_e32 v104, v104
	v_exp_f32_e32 v105, v105
	v_exp_f32_e32 v106, v106
	v_exp_f32_e32 v107, v107
	s_waitcnt lgkmcnt(2)
	v_mfma_f32_32x32x16_bf16 v[32:47], v[10:13], v[48:51], v[32:47]
	ds_read_b64_tr_b16 v[56:57], v15 offset:4608
	ds_read_b64_tr_b16 v[58:59], v15 offset:5632
	s_cmp_ge_u32 s49, s48
	s_cbranch_scc1 .Ldma2_skip
	s_cmp_gt_i32 s8, 1
	s_cselect_b32 s12, -2, 3
	s_add_i32 s12, s12, s8
	s_lshl_b32 s13, s12, 13
	s_add_i32 s13, s13, s46
	s_mov_b32 m0, s13
	s_nop 0
	global_load_lds_dwordx4 v134, s[40:41]
	s_lshl_b32 s12, s12, 14
	s_add_i32 s12, s12, s47
	s_mov_b32 m0, s12
	s_nop 0
	global_load_lds_dwordx4 v134, s[6:7]
.Ldma2_skip:
	v_exp_f32_e32 v108, v108
	v_exp_f32_e32 v109, v109
	v_exp_f32_e32 v110, v110
	v_exp_f32_e32 v111, v111
	s_waitcnt lgkmcnt(2)
	v_mfma_f32_32x32x16_bf16 v[16:31], v[6:9], v[52:55], v[16:31]
	ds_read_b64_tr_b16 v[10:11], v15 offset:6144
	ds_read_b64_tr_b16 v[12:13], v15 offset:7168
	v_exp_f32_e32 v80, v80
	v_exp_f32_e32 v81, v81
	v_exp_f32_e32 v82, v82
	v_exp_f32_e32 v83, v83
	s_waitcnt lgkmcnt(2)
	v_mfma_f32_32x32x16_bf16 v[32:47], v[6:9], v[56:59], v[32:47]
	ds_read_b64_tr_b16 v[48:49], v15 offset:6656
	ds_read_b64_tr_b16 v[50:51], v15 offset:7680
	v_exp_f32_e32 v84, v84
	v_exp_f32_e32 v85, v85
	v_exp_f32_e32 v86, v86
	v_exp_f32_e32 v87, v87
	s_waitcnt lgkmcnt(2)
	v_mfma_f32_32x32x16_bf16 v[16:31], v[2:5], v[10:13], v[16:31]
	v_exp_f32_e32 v88, v88
	v_exp_f32_e32 v89, v89
	v_exp_f32_e32 v90, v90
	v_exp_f32_e32 v91, v91
	s_waitcnt lgkmcnt(0)
	v_mfma_f32_32x32x16_bf16 v[32:47], v[2:5], v[48:51], v[32:47]
	v_exp_f32_e32 v92, v92
	v_exp_f32_e32 v93, v93
	v_exp_f32_e32 v94, v94
	v_exp_f32_e32 v95, v95
	s_add_i32 s12, s8, -4
	s_add_i32 s13, s8, 1
	s_cmp_gt_i32 s8, 3
	s_cselect_b32 s12, s12, s13
	v_lshl_add_u32 v6, s12, 13, v135
	ds_read_b128 v[2:5], v6
	ds_read_b128 v[6:9], v6 offset:512
	s_cmp_lg_u32 s8, 4
	s_cselect_b32 s54, s13, 0
	v_lshl_add_u32 v15, s54, 13, v135
	v_lshl_add_u32 v128, s8, 14, v1
	s_waitcnt lgkmcnt(1)
	v_mfma_f32_32x32x16_bf16 v[64:79], v[2:5], v[124:127], 0
	ds_read_b128 v[10:13], v15 offset:2048
	v_cvt_pk_bf16_f32 v2, v96, v97
	v_cvt_pk_bf16_f32 v3, v98, v99
	s_nop 0
	ds_read_b128 v[96:99], v15 offset:2560
	v_cvt_pk_bf16_f32 v4, v100, v101
	s_waitcnt lgkmcnt(2)
	v_mfma_f32_32x32x16_bf16 v[48:63], v[6:9], v[124:127], 0
	v_cvt_pk_bf16_f32 v5, v102, v103
	s_waitcnt lgkmcnt(1)
	v_mfma_f32_32x32x16_bf16 v[64:79], v[10:13], v[120:123], v[64:79]
	ds_read_b128 v[6:9], v15 offset:4096
	v_mfma_f32_16x16x32_bf16 v[144:147], v[2:5], v[140:143], v[144:147]
	v_cvt_pk_bf16_f32 v10, v104, v105
	v_cvt_pk_bf16_f32 v11, v106, v107
	s_waitcnt lgkmcnt(1)
	v_mfma_f32_32x32x16_bf16 v[48:63], v[96:99], v[120:123], v[48:63]
	ds_read_b128 v[100:103], v15 offset:4608
	v_cvt_pk_bf16_f32 v12, v108, v109
	v_cvt_pk_bf16_f32 v13, v110, v111
	s_waitcnt lgkmcnt(1)
	v_mfma_f32_32x32x16_bf16 v[64:79], v[6:9], v[116:119], v[64:79]
	ds_read_b128 v[96:99], v15 offset:6144
	v_mfma_f32_16x16x32_bf16 v[144:147], v[10:13], v[140:143], v[144:147]
	v_cvt_pk_bf16_f32 v6, v80, v81
	v_cvt_pk_bf16_f32 v7, v82, v83
	s_waitcnt lgkmcnt(1)
	v_mfma_f32_32x32x16_bf16 v[48:63], v[100:103], v[116:119], v[48:63]
	ds_read_b128 v[80:83], v15 offset:6656
	v_cvt_pk_bf16_f32 v8, v84, v85
	v_cvt_pk_bf16_f32 v9, v86, v87
	s_waitcnt lgkmcnt(1)
	v_mfma_f32_32x32x16_bf16 v[64:79], v[96:99], v[112:115], v[64:79]
	v_cvt_pk_bf16_f32 v84, v88, v89
	v_cvt_pk_bf16_f32 v85, v90, v91
	v_mfma_f32_16x16x32_bf16 v[144:147], v[6:9], v[140:143], v[144:147]
	ds_read_b64_tr_b16 v[88:89], v128
	ds_read_b64_tr_b16 v[90:91], v128 offset:1024
	s_waitcnt lgkmcnt(2)
	v_mfma_f32_32x32x16_bf16 v[48:63], v[80:83], v[112:115], v[48:63]
	v_cvt_pk_bf16_f32 v86, v92, v93
	v_cvt_pk_bf16_f32 v87, v94, v95
	ds_read_b64_tr_b16 v[80:81], v128 offset:512
	ds_read_b64_tr_b16 v[82:83], v128 offset:1536
	s_waitcnt lgkmcnt(2)
	v_mfma_f32_32x32x16_bf16 v[16:31], v[2:5], v[88:91], v[16:31]
	ds_read_b64_tr_b16 v[92:93], v128 offset:2048
	ds_read_b64_tr_b16 v[94:95], v128 offset:3072
	v_mfma_f32_16x16x32_bf16 v[144:147], v[84:87], v[140:143], v[144:147]
	v_exp_f32_e32 v64, v64
	v_exp_f32_e32 v65, v65
	v_exp_f32_e32 v66, v66
	v_exp_f32_e32 v67, v67
	s_waitcnt lgkmcnt(2)
	v_mfma_f32_32x32x16_bf16 v[32:47], v[2:5], v[80:83], v[32:47]
	ds_read_b64_tr_b16 v[88:89], v128 offset:2560
	ds_read_b64_tr_b16 v[90:91], v128 offset:3584
	v_exp_f32_e32 v68, v68
	v_exp_f32_e32 v69, v69
	v_exp_f32_e32 v70, v70
	v_exp_f32_e32 v71, v71
	s_waitcnt lgkmcnt(2)
	v_mfma_f32_32x32x16_bf16 v[16:31], v[10:13], v[92:95], v[16:31]
	ds_read_b64_tr_b16 v[2:3], v128 offset:4096
	ds_read_b64_tr_b16 v[4:5], v128 offset:5120
	v_exp_f32_e32 v72, v72
	v_exp_f32_e32 v73, v73
	v_exp_f32_e32 v74, v74
	v_exp_f32_e32 v75, v75
	s_waitcnt lgkmcnt(2)
	v_mfma_f32_32x32x16_bf16 v[32:47], v[10:13], v[88:91], v[32:47]
	ds_read_b64_tr_b16 v[80:81], v128 offset:4608
	ds_read_b64_tr_b16 v[82:83], v128 offset:5632
	v_exp_f32_e32 v76, v76
	v_exp_f32_e32 v77, v77
	v_exp_f32_e32 v78, v78
	v_exp_f32_e32 v79, v79
	s_waitcnt lgkmcnt(2)
	v_mfma_f32_32x32x16_bf16 v[16:31], v[6:9], v[2:5], v[16:31]
	ds_read_b64_tr_b16 v[10:11], v128 offset:6144
	ds_read_b64_tr_b16 v[12:13], v128 offset:7168
	v_exp_f32_e32 v48, v48
	v_exp_f32_e32 v49, v49
	v_exp_f32_e32 v50, v50
	v_exp_f32_e32 v51, v51
	s_waitcnt lgkmcnt(2)
	v_mfma_f32_32x32x16_bf16 v[32:47], v[6:9], v[80:83], v[32:47]
	ds_read_b64_tr_b16 v[2:3], v128 offset:6656
	ds_read_b64_tr_b16 v[4:5], v128 offset:7680
	v_exp_f32_e32 v52, v52
	v_exp_f32_e32 v53, v53
	v_exp_f32_e32 v54, v54
	v_exp_f32_e32 v55, v55
	s_waitcnt lgkmcnt(2)
	v_mfma_f32_32x32x16_bf16 v[16:31], v[84:87], v[10:13], v[16:31]
	v_exp_f32_e32 v56, v56
	v_exp_f32_e32 v57, v57
	v_exp_f32_e32 v58, v58
	v_exp_f32_e32 v59, v59
	s_waitcnt lgkmcnt(0)
	v_mfma_f32_32x32x16_bf16 v[32:47], v[84:87], v[2:5], v[32:47]
	v_exp_f32_e32 v60, v60
	v_exp_f32_e32 v61, v61
	v_exp_f32_e32 v62, v62
	v_exp_f32_e32 v63, v63
	s_add_i32 s8, s54, 1
	s_cmp_lg_u32 s54, 4
	s_cselect_b32 s8, s8, 0
	s_add_u32 s6, s6, 0x4000
	s_addc_u32 s7, s7, 0
	s_add_u32 s40, s40, 0x4000
	s_addc_u32 s41, s41, 0
	s_add_i32 s49, s49, 2
	s_lshl_b32 s12, s54, 14
	v_lshl_add_u32 v136, s8, 13, v135
	v_add_u32_e32 v15, s12, v1
	s_cmp_lt_u32 s51, s50
	s_waitcnt vmcnt(0) lgkmcnt(0)
	s_barrier
	s_cbranch_scc0 .LBB0_596
.LBB0_591:
	ds_read_b128 v[2:5], v136
	ds_read_b128 v[6:9], v136 offset:512
	s_waitcnt lgkmcnt(1)
	v_mfma_f32_32x32x16_bf16 v[96:111], v[2:5], v[124:127], 0
	ds_read_b128 v[10:13], v136 offset:2048
	v_cvt_pk_bf16_f32 v128, v64, v65
	v_cvt_pk_bf16_f32 v129, v66, v67
	s_waitcnt lgkmcnt(1)
	v_mfma_f32_32x32x16_bf16 v[80:95], v[6:9], v[124:127], 0
	ds_read_b128 v[2:5], v136 offset:2560
	v_cvt_pk_bf16_f32 v130, v68, v69
	v_cvt_pk_bf16_f32 v131, v70, v71
	s_waitcnt lgkmcnt(1)
	v_mfma_f32_32x32x16_bf16 v[96:111], v[10:13], v[120:123], v[96:111]
	ds_read_b128 v[6:9], v136 offset:4096
	v_mfma_f32_16x16x32_bf16 v[144:147], v[128:131], v[140:143], v[144:147]
	v_cvt_pk_bf16_f32 v10, v72, v73
	v_cvt_pk_bf16_f32 v11, v74, v75
	s_waitcnt lgkmcnt(1)
	v_mfma_f32_32x32x16_bf16 v[80:95], v[2:5], v[120:123], v[80:95]
	ds_read_b128 v[64:67], v136 offset:4608
	v_cvt_pk_bf16_f32 v12, v76, v77
	v_cvt_pk_bf16_f32 v13, v78, v79
	s_waitcnt lgkmcnt(1)
	v_mfma_f32_32x32x16_bf16 v[96:111], v[6:9], v[116:119], v[96:111]
	ds_read_b128 v[2:5], v136 offset:6144
	v_mfma_f32_16x16x32_bf16 v[144:147], v[10:13], v[140:143], v[144:147]
	v_cvt_pk_bf16_f32 v6, v48, v49
	v_cvt_pk_bf16_f32 v7, v50, v51
	s_waitcnt lgkmcnt(1)
	v_mfma_f32_32x32x16_bf16 v[80:95], v[64:67], v[116:119], v[80:95]
	ds_read_b128 v[68:71], v136 offset:6656
	v_cvt_pk_bf16_f32 v8, v52, v53
	v_cvt_pk_bf16_f32 v9, v54, v55
	s_waitcnt lgkmcnt(1)
	v_mfma_f32_32x32x16_bf16 v[96:111], v[2:5], v[112:115], v[96:111]
	v_cvt_pk_bf16_f32 v2, v56, v57
	v_cvt_pk_bf16_f32 v3, v58, v59
	v_mfma_f32_16x16x32_bf16 v[144:147], v[6:9], v[140:143], v[144:147]
	ds_read_b64_tr_b16 v[48:49], v15
	ds_read_b64_tr_b16 v[50:51], v15 offset:1024
	s_waitcnt lgkmcnt(2)
	v_mfma_f32_32x32x16_bf16 v[80:95], v[68:71], v[112:115], v[80:95]
	v_cvt_pk_bf16_f32 v4, v60, v61
	v_cvt_pk_bf16_f32 v5, v62, v63
	ds_read_b64_tr_b16 v[52:53], v15 offset:512
	ds_read_b64_tr_b16 v[54:55], v15 offset:1536
	s_add_i32 s51, s49, -1
	s_cmp_ge_u32 s51, s48
	s_cbranch_scc1 .LBB0_593
	s_add_u32 s12, s40, 0xffffe000
	s_addc_u32 s13, s41, -1
	s_cmp_gt_i32 s8, 2
	s_cselect_b32 s54, -3, 2
	s_add_i32 s54, s54, s8
	s_lshl_b32 s55, s54, 13
	s_add_i32 s55, s55, s46
	s_mov_b32 m0, s55
	s_nop 0
	global_load_lds_dwordx4 v134, s[12:13]
	s_add_u32 s12, s6, 0xffffe000
	s_addc_u32 s13, s7, -1
	s_lshl_b32 s54, s54, 14
	s_add_i32 s54, s54, s47
	s_mov_b32 m0, s54
	s_nop 0
	global_load_lds_dwordx4 v134, s[12:13]
.LBB0_593:
	s_branch .LBB0_590
.LBB0_595:
	s_cbranch_execz .LBB0_491
	s_branch .LBB0_599
